# v21: P2 main GEMM k-loop = ping-pong halves + LDS-DMA staging (copy issued at iteration top, retired one barrier before use)
# baseline (speedup 1.0000x reference)
;   __device__ __forceinline__ bool natural_group(int tile_row) const { return ((n0 + tile_row) >> 5) == 20; }
; template <int AMODE, int BN, class Epi>
; __device__ __forceinline__ void gemm_tile(const bf16_t* A, const int lda, const bf16_t* Bt, const int K, const int m0, const float* mu, char* lds, const Epi& epi) {
;   constexpr int WN = BN / 64, MI = WN, NBR = BN / 64, G_STAGE = (256 + BN) * G_LDT;
;   const int tid = threadIdx.x, lane = tid & 63, wid = tid >> 6, r32 = lane & 31, hi = lane >> 5;
;   const int wm = wid / WN, wn = wid % WN;
;   const int srow = tid >> 3, scc = (tid & 7) * 8;
;   int browi[NBR];
; #pragma unroll
;   for (int i = 0; i < NBR; ++i) browi[i] = 64 * i + ((Epi::PERM && !epi.natural_group(64 * i + srow)) ? ((srow & 32) + 16 * ((srow >> 2) & 1) + 4 * ((srow & 31) >> 3) + (srow & 3)) : srow);
;   f32x16 acc[MI][2];
; #pragma unroll
;   for (int i = 0; i < MI; ++i)
; #pragma unroll
;     for (int j = 0; j < 2; ++j)
; #pragma unroll
;       for (int r = 0; r < 16; ++r) acc[i][j][r] = 0.f;
;   bf16x8 ra[4], rb[NBR], rp[4], rn[4];
;   float ssq[4] = {0.f, 0.f, 0.f, 0.f};
;   int dprev[4], dnext[4];
;   if constexpr (AMODE == 1) {
;     const int t0 = m0 % TL;
; #pragma unroll
;     for (int i = 0; i < 4; ++i) { const int t = t0 + srow + 64 * i; dprev[i] = (t != 0 && t != T) ? 1 : 0; dnext[i] = (t != T - 1 && t != TL - 1) ? 1 : 0; }
;   }
;   auto gload = [&](int k0) {
; #pragma unroll
;     for (int i = 0; i < 4; ++i) {
;       const bf16_t* ap = A + (size_t)(m0 + srow + 64 * i) * lda + k0 + scc;
;       ra[i] = *(const bf16x8*)ap;
;       if constexpr (AMODE == 1) { rp[i] = *(const bf16x8*)(ap - dprev[i] * lda); rn[i] = *(const bf16x8*)(ap + dnext[i] * lda); }
;     }
; #pragma unroll
;     for (int i = 0; i < NBR; ++i) rb[i] = *(const bf16x8*)(Bt + (size_t)browi[i] * K + k0 + scc);
;   };
.LBB0_407:
	v_or_b32_e32 v0, s20, v161
	v_ashrrev_i32_e32 v1, 31, v0
	v_lshlrev_b64 v[48:49], 11, v[0:1]
	v_lshl_add_u64 v[2:3], s[16:17], 0, v[48:49]
	v_lshl_add_u64 v[52:53], v[48:49], 0, s[14:15]
	s_lshl_b32 s18, s48, 8
	v_lshl_add_u64 v[50:51], v[2:3], 0, v[170:171]
	v_lshl_add_u64 v[2:3], s[16:17], 0, v[52:53]
	s_and_b32 s21, s18, 0x300
	s_lshl_b32 s18, s4, 10
	v_lshl_add_u64 v[54:55], v[2:3], 0, v[170:171]
	v_or_b32_e32 v2, 0x80, v0
	v_add_u32_e32 v0, 0xc0, v0
	s_or_b32 s18, s21, s18
	v_ashrrev_i32_e32 v1, 31, v0
	s_ashr_i32 s19, s18, 31
	v_lshlrev_b64 v[60:61], 11, v[0:1]
	s_lshl_b64 s[18:19], s[18:19], 11
	v_lshl_add_u64 v[0:1], s[16:17], 0, v[60:61]
	v_lshl_add_u64 v[62:63], v[0:1], 0, v[170:171]
	v_lshl_add_u64 v[0:1], v[164:165], 0, s[18:19]
	v_lshl_add_u64 v[64:65], v[0:1], 0, v[170:171]
	v_add_co_u32_e32 v66, vcc, s34, v64
	v_ashrrev_i32_e32 v3, 31, v2
	s_nop 0
	v_addc_co_u32_e32 v67, vcc, 0, v65, vcc
	v_add_co_u32_e32 v68, vcc, s35, v64
	v_lshlrev_b64 v[56:57], 11, v[2:3]
	s_nop 0
	v_addc_co_u32_e32 v69, vcc, 0, v65, vcc
	v_lshl_add_u64 v[2:3], s[16:17], 0, v[56:57]
	v_add_co_u32_e32 v70, vcc, s43, v64
	v_lshl_add_u64 v[58:59], v[2:3], 0, v[170:171]
	s_nop 0
	v_addc_co_u32_e32 v71, vcc, 0, v65, vcc
	global_load_dwordx4 v[16:19], v[50:51], off
	global_load_dwordx4 v[128:131], v[50:51], off offset:128
	global_load_dwordx4 v[20:23], v[54:55], off
	global_load_dwordx4 v[24:27], v[58:59], off
	global_load_dwordx4 v[28:31], v[62:63], off
	global_load_dwordx4 v[32:35], v[64:65], off
	global_load_dwordx4 v[36:39], v[66:67], off
	global_load_dwordx4 v[40:43], v[68:69], off
	global_load_dwordx4 v[44:47], v[70:71], off
	global_load_dwordx4 v[132:135], v[54:55], off offset:128
	global_load_dwordx4 v[136:139], v[58:59], off offset:128
	global_load_dwordx4 v[140:143], v[62:63], off offset:128
	global_load_dwordx4 v[144:147], v[64:65], off offset:128
	global_load_dwordx4 v[148:151], v[66:67], off offset:128
	global_load_dwordx4 v[152:155], v[68:69], off offset:128
	global_load_dwordx4 v[156:159], v[70:71], off offset:128
	s_lshl_b32 s72, s20, 11
	s_add_u32 s66, s16, s72
	s_addc_u32 s67, s17, 0
	s_add_u32 s66, s66, 0x80
	s_addc_u32 s67, s67, 0
	v_mov_b32_e32 v0, 0
	s_mov_b32 s22, 0
	s_mov_b64 s[16:17], 0
	v_mov_b32_e32 v1, v0
	v_mov_b32_e32 v2, v0
	v_mov_b32_e32 v3, v0
	v_mov_b32_e32 v4, v0
	v_mov_b32_e32 v5, v0
	v_mov_b32_e32 v6, v0
	v_mov_b32_e32 v7, v0
	v_mov_b32_e32 v8, v0
	v_mov_b32_e32 v9, v0
	v_mov_b32_e32 v10, v0
	v_mov_b32_e32 v11, v0
	v_mov_b32_e32 v12, v0
	v_mov_b32_e32 v13, v0
	v_mov_b32_e32 v14, v0
	v_mov_b32_e32 v15, v0
	s_add_u32 s68, s86, s18
	s_addc_u32 s69, s87, s19
	s_add_u32 s68, s68, 0x3c540080
	s_addc_u32 s69, s69, 0
	v_readfirstlane_b32 s96, v182
	s_nop 0
	s_cmp_lt_u32 s96, 4
	s_cselect_b32 s72, s66, s68
	s_cselect_b32 s73, s67, s69
	s_lshl_b32 s92, s96, 6
	s_lshl_b32 s96, s96, 10
	v_and_b32_e32 v48, 63, v178
	v_add_u32_e32 v48, s92, v48
	s_nop 0
	v_mul_u32_u24_e32 v50, 0x1c72, v48
	v_lshrrev_b32_e32 v50, 16, v50
	v_mul_u32_u24_e32 v51, 9, v50
	v_sub_u32_e32 v51, v48, v51
	v_lshlrev_b32_e32 v52, 11, v50
	v_lshl_add_u32 v52, v51, 4, v52
	v_and_b32_e32 v53, 0xe3, v50
	v_bfe_u32 v54, v50, 2, 1
	v_lshl_or_b32 v53, v54, 4, v53
	v_bfe_u32 v54, v50, 3, 2
	v_lshl_or_b32 v53, v54, 2, v53
	v_lshlrev_b32_e32 v53, 11, v53
	v_lshl_add_u32 v53, v51, 4, v53
	v_cmp_lt_u32_e32 vcc, 0xff, v50
	v_cndmask_b32_e32 v52, v52, v53, vcc
	v_cmp_eq_u32_e32 vcc, 8, v51
	v_cndmask_b32_e64 v194, v52, 0, vcc
	v_add_u32_e32 v49, 0x200, v48
	v_mul_u32_u24_e32 v50, 0x1c72, v49
	v_lshrrev_b32_e32 v50, 16, v50
	v_mul_u32_u24_e32 v51, 9, v50
	v_sub_u32_e32 v51, v49, v51
	v_lshlrev_b32_e32 v52, 11, v50
	v_lshl_add_u32 v52, v51, 4, v52
	v_and_b32_e32 v53, 0xe3, v50
	v_bfe_u32 v54, v50, 2, 1
	v_lshl_or_b32 v53, v54, 4, v53
	v_bfe_u32 v54, v50, 3, 2
	v_lshl_or_b32 v53, v54, 2, v53
	v_lshlrev_b32_e32 v53, 11, v53
	v_lshl_add_u32 v53, v51, 4, v53
	v_cmp_lt_u32_e32 vcc, 0xff, v50
	v_cndmask_b32_e32 v52, v52, v53, vcc
	v_cmp_eq_u32_e32 vcc, 8, v51
	v_cndmask_b32_e64 v195, v52, 0, vcc
	v_add_u32_e32 v49, 0x400, v48
	v_mul_u32_u24_e32 v50, 0x1c72, v49
	v_lshrrev_b32_e32 v50, 16, v50
	v_mul_u32_u24_e32 v51, 9, v50
	v_sub_u32_e32 v51, v49, v51
	v_lshlrev_b32_e32 v52, 11, v50
	v_lshl_add_u32 v52, v51, 4, v52
	v_and_b32_e32 v53, 0xe3, v50
	v_bfe_u32 v54, v50, 2, 1
	v_lshl_or_b32 v53, v54, 4, v53
	v_bfe_u32 v54, v50, 3, 2
	v_lshl_or_b32 v53, v54, 2, v53
	v_lshlrev_b32_e32 v53, 11, v53
	v_lshl_add_u32 v53, v51, 4, v53
	v_cmp_lt_u32_e32 vcc, 0xff, v50
	v_cndmask_b32_e32 v52, v52, v53, vcc
	v_cmp_eq_u32_e32 vcc, 8, v51
	v_cndmask_b32_e64 v196, v52, 0, vcc
	v_add_u32_e32 v49, 0x600, v48
	v_mul_u32_u24_e32 v50, 0x1c72, v49
	v_lshrrev_b32_e32 v50, 16, v50
	v_mul_u32_u24_e32 v51, 9, v50
	v_sub_u32_e32 v51, v49, v51
	v_lshlrev_b32_e32 v52, 11, v50
	v_lshl_add_u32 v52, v51, 4, v52
	v_and_b32_e32 v53, 0xe3, v50
	v_bfe_u32 v54, v50, 2, 1
	v_lshl_or_b32 v53, v54, 4, v53
	v_bfe_u32 v54, v50, 3, 2
	v_lshl_or_b32 v53, v54, 2, v53
	v_lshlrev_b32_e32 v53, 11, v53
	v_lshl_add_u32 v53, v51, 4, v53
	v_cmp_lt_u32_e32 vcc, 0xff, v50
	v_cndmask_b32_e32 v52, v52, v53, vcc
	v_cmp_eq_u32_e32 vcc, 8, v51
	v_cndmask_b32_e64 v197, v52, 0, vcc
	v_add_u32_e32 v49, 0x800, v48
	v_mul_u32_u24_e32 v50, 0x1c72, v49
	v_lshrrev_b32_e32 v50, 16, v50
	v_mul_u32_u24_e32 v51, 9, v50
	v_sub_u32_e32 v51, v49, v51
	v_lshlrev_b32_e32 v52, 11, v50
	v_lshl_add_u32 v52, v51, 4, v52
	v_and_b32_e32 v53, 0xe3, v50
	v_bfe_u32 v54, v50, 2, 1
	v_lshl_or_b32 v53, v54, 4, v53
	v_bfe_u32 v54, v50, 3, 2
	v_lshl_or_b32 v53, v54, 2, v53
	v_lshlrev_b32_e32 v53, 11, v53
	v_lshl_add_u32 v53, v51, 4, v53
	v_cmp_lt_u32_e32 vcc, 0xff, v50
; template <int AMODE, int BN, class Epi>
; __device__ __forceinline__ void gemm_tile(const bf16_t* A, const int lda, const bf16_t* Bt, const int K, const int m0, const float* mu, char* lds, const Epi& epi) {
;     ...
;   f32x16 acc[MI][2];
; #pragma unroll
;   for (int i = 0; i < MI; ++i)
; #pragma unroll
;     for (int j = 0; j < 2; ++j)
; #pragma unroll
;       for (int r = 0; r < 16; ++r) acc[i][j][r] = 0.f;
;     ...
;   gload(0);
;   lstore(0, 0);
;   if (nk > 1) gload(64);
;   __syncthreads();
	v_cndmask_b32_e32 v52, v52, v53, vcc
	v_cmp_eq_u32_e32 vcc, 8, v51
	v_cndmask_b32_e64 v198, v52, 0, vcc
	v_add_u32_e32 v49, 0xa00, v48
	v_mul_u32_u24_e32 v50, 0x1c72, v49
	v_lshrrev_b32_e32 v50, 16, v50
	v_mul_u32_u24_e32 v51, 9, v50
	v_sub_u32_e32 v51, v49, v51
	v_lshlrev_b32_e32 v52, 11, v50
	v_lshl_add_u32 v52, v51, 4, v52
	v_and_b32_e32 v53, 0xe3, v50
	v_bfe_u32 v54, v50, 2, 1
	v_lshl_or_b32 v53, v54, 4, v53
	v_bfe_u32 v54, v50, 3, 2
	v_lshl_or_b32 v53, v54, 2, v53
	v_lshlrev_b32_e32 v53, 11, v53
	v_lshl_add_u32 v53, v51, 4, v53
	v_cmp_lt_u32_e32 vcc, 0xff, v50
	v_cndmask_b32_e32 v52, v52, v53, vcc
	v_cmp_eq_u32_e32 vcc, 8, v51
	v_cndmask_b32_e64 v199, v52, 0, vcc
	v_add_u32_e32 v49, 0xc00, v48
	v_mul_u32_u24_e32 v50, 0x1c72, v49
	v_lshrrev_b32_e32 v50, 16, v50
	v_mul_u32_u24_e32 v51, 9, v50
	v_sub_u32_e32 v51, v49, v51
	v_lshlrev_b32_e32 v52, 11, v50
	v_lshl_add_u32 v52, v51, 4, v52
	v_and_b32_e32 v53, 0xe3, v50
	v_bfe_u32 v54, v50, 2, 1
	v_lshl_or_b32 v53, v54, 4, v53
	v_bfe_u32 v54, v50, 3, 2
	v_lshl_or_b32 v53, v54, 2, v53
	v_lshlrev_b32_e32 v53, 11, v53
	v_lshl_add_u32 v53, v51, 4, v53
	v_cmp_lt_u32_e32 vcc, 0xff, v50
	v_cndmask_b32_e32 v52, v52, v53, vcc
	v_cmp_eq_u32_e32 vcc, 8, v51
	v_cndmask_b32_e64 v200, v52, 0, vcc
	v_add_u32_e32 v49, 0xe00, v48
	v_mul_u32_u24_e32 v50, 0x1c72, v49
	v_lshrrev_b32_e32 v50, 16, v50
	v_mul_u32_u24_e32 v51, 9, v50
	v_sub_u32_e32 v51, v49, v51
	v_lshlrev_b32_e32 v52, 11, v50
	v_lshl_add_u32 v52, v51, 4, v52
	v_and_b32_e32 v53, 0xe3, v50
	v_bfe_u32 v54, v50, 2, 1
	v_lshl_or_b32 v53, v54, 4, v53
	v_bfe_u32 v54, v50, 3, 2
	v_lshl_or_b32 v53, v54, 2, v53
	v_lshlrev_b32_e32 v53, 11, v53
	v_lshl_add_u32 v53, v51, 4, v53
	v_cmp_lt_u32_e32 vcc, 0xff, v50
	v_cndmask_b32_e32 v52, v52, v53, vcc
	v_cmp_eq_u32_e32 vcc, 8, v51
	v_cndmask_b32_e64 v201, v52, 0, vcc
	v_add_u32_e32 v49, 0x1000, v48
	v_mul_u32_u24_e32 v50, 0x1c72, v49
	v_lshrrev_b32_e32 v50, 16, v50
	v_mul_u32_u24_e32 v51, 9, v50
	v_sub_u32_e32 v51, v49, v51
	v_lshlrev_b32_e32 v52, 11, v50
	v_lshl_add_u32 v52, v51, 4, v52
	v_and_b32_e32 v53, 0xe3, v50
	v_bfe_u32 v54, v50, 2, 1
	v_lshl_or_b32 v53, v54, 4, v53
	v_bfe_u32 v54, v50, 3, 2
	v_lshl_or_b32 v53, v54, 2, v53
	v_lshlrev_b32_e32 v53, 11, v53
	v_lshl_add_u32 v53, v51, 4, v53
	v_cmp_lt_u32_e32 vcc, 0xff, v50
	v_cndmask_b32_e32 v52, v52, v53, vcc
	v_cmp_eq_u32_e32 vcc, 8, v51
	v_cndmask_b32_e64 v202, v52, 0, vcc
	v_mov_b32_e32 v48, v0
	v_mov_b32_e32 v49, v0
	v_mov_b32_e32 v50, v0
	v_mov_b32_e32 v51, v0
	v_mov_b32_e32 v52, v0
	v_mov_b32_e32 v53, v0
	v_mov_b32_e32 v54, v0
	v_mov_b32_e32 v55, v0
	v_mov_b32_e32 v56, v0
	v_mov_b32_e32 v57, v0
	v_mov_b32_e32 v58, v0
	v_mov_b32_e32 v59, v0
	v_mov_b32_e32 v60, v0
	v_mov_b32_e32 v61, v0
	v_mov_b32_e32 v62, v0
	v_mov_b32_e32 v63, v0
	v_mov_b32_e32 v64, v0
	v_mov_b32_e32 v65, v0
	s_waitcnt vmcnt(15)
	ds_write_b128 v185, v[16:19]
	s_waitcnt vmcnt(13)
	ds_write_b128 v185, v[20:23] offset:9216
	s_waitcnt vmcnt(12)
	ds_write_b128 v185, v[24:27] offset:18432
	s_waitcnt vmcnt(11)
	ds_write_b128 v185, v[28:31] offset:27648
	s_waitcnt vmcnt(10)
	ds_write_b128 v185, v[32:35] offset:36864
	s_waitcnt vmcnt(9)
	ds_write_b128 v185, v[36:39] offset:46080
	s_waitcnt vmcnt(8)
	ds_write_b128 v185, v[40:43] offset:55296
	s_waitcnt vmcnt(7)
	ds_write_b128 v185, v[44:47] offset:64512
	v_mov_b32_e32 v16, v0
	v_mov_b32_e32 v17, v0
	v_mov_b32_e32 v18, v0
	v_mov_b32_e32 v19, v0
	v_mov_b32_e32 v20, v0
	v_mov_b32_e32 v21, v0
	v_mov_b32_e32 v22, v0
	v_mov_b32_e32 v23, v0
	v_mov_b32_e32 v24, v0
	v_mov_b32_e32 v25, v0
	v_mov_b32_e32 v26, v0
	v_mov_b32_e32 v27, v0
	v_mov_b32_e32 v28, v0
	v_mov_b32_e32 v29, v0
	v_mov_b32_e32 v30, v0
	v_mov_b32_e32 v31, v0
	v_mov_b32_e32 v32, v0
	v_mov_b32_e32 v33, v0
	v_mov_b32_e32 v34, v0
	v_mov_b32_e32 v35, v0
	v_mov_b32_e32 v36, v0
	v_mov_b32_e32 v37, v0
	v_mov_b32_e32 v38, v0
	v_mov_b32_e32 v39, v0
	v_mov_b32_e32 v40, v0
	v_mov_b32_e32 v41, v0
	v_mov_b32_e32 v42, v0
	v_mov_b32_e32 v43, v0
	v_mov_b32_e32 v44, v0
	v_mov_b32_e32 v45, v0
	v_mov_b32_e32 v46, v0
	v_mov_b32_e32 v47, v0
	v_mov_b32_e32 v66, v0
	v_mov_b32_e32 v67, v0
	v_mov_b32_e32 v68, v0
	v_mov_b32_e32 v69, v0
	v_mov_b32_e32 v70, v0
	v_mov_b32_e32 v71, v0
	v_mov_b32_e32 v72, v0
	v_mov_b32_e32 v73, v0
	v_mov_b32_e32 v74, v0
	v_mov_b32_e32 v75, v0
	v_mov_b32_e32 v76, v0
	v_mov_b32_e32 v77, v0
	v_mov_b32_e32 v78, v0
	v_mov_b32_e32 v79, v0
	v_mov_b32_e32 v80, v0
	v_mov_b32_e32 v81, v0
	v_mov_b32_e32 v82, v0
	v_mov_b32_e32 v83, v0
	v_mov_b32_e32 v84, v0
	v_mov_b32_e32 v85, v0
	v_mov_b32_e32 v86, v0
	v_mov_b32_e32 v87, v0
	v_mov_b32_e32 v88, v0
	v_mov_b32_e32 v89, v0
	v_mov_b32_e32 v90, v0
	v_mov_b32_e32 v91, v0
	v_mov_b32_e32 v92, v0
	v_mov_b32_e32 v93, v0
	v_mov_b32_e32 v94, v0
	v_mov_b32_e32 v95, v0
	v_mov_b32_e32 v96, v0
	v_mov_b32_e32 v97, v0
	v_mov_b32_e32 v98, v0
	v_mov_b32_e32 v99, v0
	v_mov_b32_e32 v100, v0
	v_mov_b32_e32 v101, v0
	v_mov_b32_e32 v102, v0
	v_mov_b32_e32 v103, v0
	v_mov_b32_e32 v104, v0
	v_mov_b32_e32 v105, v0
	v_mov_b32_e32 v106, v0
	v_mov_b32_e32 v107, v0
	v_mov_b32_e32 v108, v0
	v_mov_b32_e32 v109, v0
	v_mov_b32_e32 v110, v0
	v_mov_b32_e32 v111, v0
	v_mov_b32_e32 v112, v0
	v_mov_b32_e32 v113, v0
	v_mov_b32_e32 v114, v0
	v_mov_b32_e32 v115, v0
	v_mov_b32_e32 v116, v0
	v_mov_b32_e32 v117, v0
	v_mov_b32_e32 v118, v0
	v_mov_b32_e32 v119, v0
	v_mov_b32_e32 v120, v0
	v_mov_b32_e32 v121, v0
	v_mov_b32_e32 v122, v0
	v_mov_b32_e32 v123, v0
	v_mov_b32_e32 v124, v0
	v_mov_b32_e32 v125, v0
	v_mov_b32_e32 v126, v0
	v_mov_b32_e32 v127, v0
	s_waitcnt lgkmcnt(0)
	s_barrier
	v_readfirstlane_b32 s61, v178
	s_nop 0
	s_cmpk_lt_u32 s61, 0x100
	s_cbranch_scc0 .LpdP2_B

; #define MFMA(a, b, c) __builtin_amdgcn_mfma_f32_32x32x16_bf16((a), (b), (c), 0, 0, 0)
; template <int AMODE, int BN, class Epi>
; __device__ __forceinline__ void gemm_tile(const bf16_t* A, const int lda, const bf16_t* Bt, const int K, const int m0, const float* mu, char* lds, const Epi& epi) {
;     ...
; #pragma unroll 1
;   for (int kt = 0; kt < nk; ++kt) {
;     const int s = kt & 1;
;     if (kt + 1 < nk) lstore(s ^ 1, (kt + 1) * 64);
;     if (kt + 2 < nk) gload((kt + 2) * 64);
;     {
;       const char* Ab = lds + s * G_STAGE + (wm * (32 * MI) + r32) * G_LDT + hi * 16;
;       const char* Bb = lds + s * G_STAGE + 256 * G_LDT + (wn * 64 + r32) * G_LDT + hi * 16;
;       bf16x8 fb[2][2], fa[2][MI];
;       fb[0][0] = *(const bf16x8*)(Bb); fb[0][1] = *(const bf16x8*)(Bb + 32 * G_LDT);
; #pragma unroll
;       for (int mi = 0; mi < MI; ++mi) fa[0][mi] = *(const bf16x8*)(Ab + mi * 32 * G_LDT);
; #pragma unroll
;       for (int ks = 0; ks < 4; ++ks) {
;         const int sl = ks & 1;
;         if (ks + 1 < 4) {
;           fb[sl ^ 1][0] = *(const bf16x8*)(Bb + (ks + 1) * 32); fb[sl ^ 1][1] = *(const bf16x8*)(Bb + 32 * G_LDT + (ks + 1) * 32);
; #pragma unroll
;           for (int mi = 0; mi < MI; ++mi) fa[sl ^ 1][mi] = *(const bf16x8*)(Ab + mi * 32 * G_LDT + (ks + 1) * 32);
;         }
; #pragma unroll
;         for (int mi = 0; mi < MI; ++mi) { acc[mi][0] = MFMA(fb[sl][0], fa[sl][mi], acc[mi][0]); acc[mi][1] = MFMA(fb[sl][1], fa[sl][mi], acc[mi][1]); }
;       }
;     }
;     __syncthreads();
;   }
.LpdP2_noA:
	s_mul_i32 s18, s18, 0x12000
	s_add_i32 s18, s18, 0
	v_add3_u32 v173, s18, v205, v177
	ds_read_b128 v[212:215], v173 offset:36864
	v_add3_u32 v175, s18, v204, v177
	ds_read_b128 v[216:219], v175
	ds_read_b128 v[220:223], v173 offset:36896
	ds_read_b128 v[228:231], v175 offset:32
	ds_read_b128 v[232:235], v173 offset:41472
	ds_read_b128 v[236:239], v173 offset:41504
	s_waitcnt lgkmcnt(1)
	v_mfma_f32_32x32x16_bf16 v[96:111], v[232:235], v[216:219], v[96:111]
	v_mfma_f32_32x32x16_bf16 v[112:127], v[212:215], v[216:219], v[112:127]
	ds_read_b128 v[216:219], v175 offset:4608
	ds_read_b128 v[240:243], v175 offset:4640
	s_waitcnt lgkmcnt(1)
	v_mfma_f32_32x32x16_bf16 v[80:95], v[212:215], v[216:219], v[80:95]
	v_mfma_f32_32x32x16_bf16 v[64:79], v[232:235], v[216:219], v[64:79]
	ds_read_b128 v[216:219], v175 offset:9216
	ds_read_b128 v[244:247], v175 offset:9248
	s_waitcnt lgkmcnt(1)
	v_mfma_f32_32x32x16_bf16 v[48:63], v[212:215], v[216:219], v[48:63]
	v_mfma_f32_32x32x16_bf16 v[32:47], v[232:235], v[216:219], v[32:47]
	ds_read_b128 v[216:219], v175 offset:13824
	ds_read_b128 v[248:251], v175 offset:13856
	s_waitcnt lgkmcnt(1)
	v_mfma_f32_32x32x16_bf16 v[16:31], v[212:215], v[216:219], v[16:31]
	v_mfma_f32_32x32x16_bf16 v[0:15], v[232:235], v[216:219], v[0:15]
	v_mfma_f32_32x32x16_bf16 v[112:127], v[220:223], v[228:231], v[112:127]
	v_mfma_f32_32x32x16_bf16 v[96:111], v[236:239], v[228:231], v[96:111]
	v_mfma_f32_32x32x16_bf16 v[80:95], v[220:223], v[240:243], v[80:95]
	v_mfma_f32_32x32x16_bf16 v[64:79], v[236:239], v[240:243], v[64:79]
	v_mfma_f32_32x32x16_bf16 v[48:63], v[220:223], v[244:247], v[48:63]
	v_mfma_f32_32x32x16_bf16 v[32:47], v[236:239], v[244:247], v[32:47]
	s_waitcnt lgkmcnt(0)
	v_mfma_f32_32x32x16_bf16 v[16:31], v[220:223], v[248:251], v[16:31]
	ds_read_b128 v[212:215], v173 offset:36928
	ds_read_b128 v[216:219], v175 offset:64
	ds_read_b128 v[220:223], v173 offset:36960
	ds_read_b128 v[228:231], v175 offset:96
	v_mfma_f32_32x32x16_bf16 v[0:15], v[236:239], v[248:251], v[0:15]
	ds_read_b128 v[232:235], v173 offset:41536
	ds_read_b128 v[236:239], v173 offset:41568
	s_waitcnt lgkmcnt(4)
	v_mfma_f32_32x32x16_bf16 v[112:127], v[212:215], v[216:219], v[112:127]
	s_waitcnt lgkmcnt(1)
	v_mfma_f32_32x32x16_bf16 v[96:111], v[232:235], v[216:219], v[96:111]
	ds_read_b128 v[216:219], v175 offset:4672
	ds_read_b128 v[240:243], v175 offset:4704
	s_waitcnt lgkmcnt(1)
	v_mfma_f32_32x32x16_bf16 v[80:95], v[212:215], v[216:219], v[80:95]
	v_mfma_f32_32x32x16_bf16 v[64:79], v[232:235], v[216:219], v[64:79]
	ds_read_b128 v[216:219], v175 offset:9280
	ds_read_b128 v[244:247], v175 offset:9312
	s_waitcnt lgkmcnt(1)
	v_mfma_f32_32x32x16_bf16 v[48:63], v[212:215], v[216:219], v[48:63]
	v_mfma_f32_32x32x16_bf16 v[32:47], v[232:235], v[216:219], v[32:47]
	ds_read_b128 v[216:219], v175 offset:13888
	ds_read_b128 v[248:251], v175 offset:13920
	s_waitcnt lgkmcnt(0)
	s_barrier
	v_mfma_f32_32x32x16_bf16 v[16:31], v[212:215], v[216:219], v[16:31]
	v_mfma_f32_32x32x16_bf16 v[0:15], v[232:235], v[216:219], v[0:15]
	v_mfma_f32_32x32x16_bf16 v[112:127], v[220:223], v[228:231], v[112:127]
	v_mfma_f32_32x32x16_bf16 v[96:111], v[236:239], v[228:231], v[96:111]
	v_mfma_f32_32x32x16_bf16 v[80:95], v[220:223], v[240:243], v[80:95]
	v_mfma_f32_32x32x16_bf16 v[64:79], v[236:239], v[240:243], v[64:79]
	v_mfma_f32_32x32x16_bf16 v[48:63], v[220:223], v[244:247], v[48:63]
	v_mfma_f32_32x32x16_bf16 v[32:47], v[236:239], v[244:247], v[32:47]
	v_mfma_f32_32x32x16_bf16 v[16:31], v[220:223], v[248:251], v[16:31]
	v_mfma_f32_32x32x16_bf16 v[0:15], v[236:239], v[248:251], v[0:15]
	s_waitcnt vmcnt(0)
	s_barrier
	s_add_u32 s16, s16, 0x80
	s_addc_u32 s17, s17, 0
	s_add_i32 s22, s22, 1
	s_cmpk_lg_i32 s16, 0x800
	s_cbranch_scc1 .LpdP2_A
	s_branch .LBB0_394

; #define MFMA(a, b, c) __builtin_amdgcn_mfma_f32_32x32x16_bf16((a), (b), (c), 0, 0, 0)
; template <int AMODE, int BN, class Epi>
; __device__ __forceinline__ void gemm_tile(const bf16_t* A, const int lda, const bf16_t* Bt, const int K, const int m0, const float* mu, char* lds, const Epi& epi) {
;     ...
; #pragma unroll 1
;   for (int kt = 0; kt < nk; ++kt) {
;     const int s = kt & 1;
;     if (kt + 1 < nk) lstore(s ^ 1, (kt + 1) * 64);
;     if (kt + 2 < nk) gload((kt + 2) * 64);
;     {
;       const char* Ab = lds + s * G_STAGE + (wm * (32 * MI) + r32) * G_LDT + hi * 16;
;       const char* Bb = lds + s * G_STAGE + 256 * G_LDT + (wn * 64 + r32) * G_LDT + hi * 16;
;       bf16x8 fb[2][2], fa[2][MI];
;       fb[0][0] = *(const bf16x8*)(Bb); fb[0][1] = *(const bf16x8*)(Bb + 32 * G_LDT);
; #pragma unroll
;       for (int mi = 0; mi < MI; ++mi) fa[0][mi] = *(const bf16x8*)(Ab + mi * 32 * G_LDT);
; #pragma unroll
;       for (int ks = 0; ks < 4; ++ks) {
;         const int sl = ks & 1;
;         if (ks + 1 < 4) {
;           fb[sl ^ 1][0] = *(const bf16x8*)(Bb + (ks + 1) * 32); fb[sl ^ 1][1] = *(const bf16x8*)(Bb + 32 * G_LDT + (ks + 1) * 32);
; #pragma unroll
;           for (int mi = 0; mi < MI; ++mi) fa[sl ^ 1][mi] = *(const bf16x8*)(Ab + mi * 32 * G_LDT + (ks + 1) * 32);
;         }
; #pragma unroll
;         for (int mi = 0; mi < MI; ++mi) { acc[mi][0] = MFMA(fb[sl][0], fa[sl][mi], acc[mi][0]); acc[mi][1] = MFMA(fb[sl][1], fa[sl][mi], acc[mi][1]); }
;       }
;     }
;     __syncthreads();
;   }
.LpdP2_noB:
	s_barrier
	s_mul_i32 s18, s18, 0x12000
	s_add_i32 s18, s18, 0
	v_add3_u32 v173, s18, v205, v177
	ds_read_b128 v[212:215], v173 offset:36864
	v_add3_u32 v175, s18, v204, v177
	ds_read_b128 v[216:219], v175
	ds_read_b128 v[220:223], v173 offset:36896
	ds_read_b128 v[228:231], v175 offset:32
	ds_read_b128 v[232:235], v173 offset:41472
	ds_read_b128 v[236:239], v173 offset:41504
	s_waitcnt lgkmcnt(1)
	v_mfma_f32_32x32x16_bf16 v[96:111], v[232:235], v[216:219], v[96:111]
	v_mfma_f32_32x32x16_bf16 v[112:127], v[212:215], v[216:219], v[112:127]
	ds_read_b128 v[216:219], v175 offset:4608
	ds_read_b128 v[240:243], v175 offset:4640
	s_waitcnt lgkmcnt(1)
	v_mfma_f32_32x32x16_bf16 v[80:95], v[212:215], v[216:219], v[80:95]
	v_mfma_f32_32x32x16_bf16 v[64:79], v[232:235], v[216:219], v[64:79]
	ds_read_b128 v[216:219], v175 offset:9216
	ds_read_b128 v[244:247], v175 offset:9248
	s_waitcnt lgkmcnt(1)
	v_mfma_f32_32x32x16_bf16 v[48:63], v[212:215], v[216:219], v[48:63]
	v_mfma_f32_32x32x16_bf16 v[32:47], v[232:235], v[216:219], v[32:47]
	ds_read_b128 v[216:219], v175 offset:13824
	ds_read_b128 v[248:251], v175 offset:13856
	s_waitcnt lgkmcnt(1)
	v_mfma_f32_32x32x16_bf16 v[16:31], v[212:215], v[216:219], v[16:31]
	v_mfma_f32_32x32x16_bf16 v[0:15], v[232:235], v[216:219], v[0:15]
	v_mfma_f32_32x32x16_bf16 v[112:127], v[220:223], v[228:231], v[112:127]
	v_mfma_f32_32x32x16_bf16 v[96:111], v[236:239], v[228:231], v[96:111]
	v_mfma_f32_32x32x16_bf16 v[80:95], v[220:223], v[240:243], v[80:95]
	v_mfma_f32_32x32x16_bf16 v[64:79], v[236:239], v[240:243], v[64:79]
	v_mfma_f32_32x32x16_bf16 v[48:63], v[220:223], v[244:247], v[48:63]
	v_mfma_f32_32x32x16_bf16 v[32:47], v[236:239], v[244:247], v[32:47]
	s_waitcnt lgkmcnt(0)
	v_mfma_f32_32x32x16_bf16 v[16:31], v[220:223], v[248:251], v[16:31]
	ds_read_b128 v[212:215], v173 offset:36928
	ds_read_b128 v[216:219], v175 offset:64
	ds_read_b128 v[220:223], v173 offset:36960
	ds_read_b128 v[228:231], v175 offset:96
	v_mfma_f32_32x32x16_bf16 v[0:15], v[236:239], v[248:251], v[0:15]
	ds_read_b128 v[232:235], v173 offset:41536
	ds_read_b128 v[236:239], v173 offset:41568
	s_waitcnt lgkmcnt(4)
	v_mfma_f32_32x32x16_bf16 v[112:127], v[212:215], v[216:219], v[112:127]
	s_waitcnt lgkmcnt(1)
	v_mfma_f32_32x32x16_bf16 v[96:111], v[232:235], v[216:219], v[96:111]
	ds_read_b128 v[216:219], v175 offset:4672
	ds_read_b128 v[240:243], v175 offset:4704
	s_waitcnt lgkmcnt(1)
	v_mfma_f32_32x32x16_bf16 v[80:95], v[212:215], v[216:219], v[80:95]
	v_mfma_f32_32x32x16_bf16 v[64:79], v[232:235], v[216:219], v[64:79]
	ds_read_b128 v[216:219], v175 offset:9280
	ds_read_b128 v[244:247], v175 offset:9312
	s_waitcnt lgkmcnt(1)
	v_mfma_f32_32x32x16_bf16 v[48:63], v[212:215], v[216:219], v[48:63]
	v_mfma_f32_32x32x16_bf16 v[32:47], v[232:235], v[216:219], v[32:47]
	ds_read_b128 v[216:219], v175 offset:13888
	ds_read_b128 v[248:251], v175 offset:13920
	s_waitcnt vmcnt(0) lgkmcnt(0)
	s_barrier
	v_mfma_f32_32x32x16_bf16 v[16:31], v[212:215], v[216:219], v[16:31]
	v_mfma_f32_32x32x16_bf16 v[0:15], v[232:235], v[216:219], v[0:15]
	v_mfma_f32_32x32x16_bf16 v[112:127], v[220:223], v[228:231], v[112:127]
	v_mfma_f32_32x32x16_bf16 v[96:111], v[236:239], v[228:231], v[96:111]
	v_mfma_f32_32x32x16_bf16 v[80:95], v[220:223], v[240:243], v[80:95]
	v_mfma_f32_32x32x16_bf16 v[64:79], v[236:239], v[240:243], v[64:79]
	v_mfma_f32_32x32x16_bf16 v[48:63], v[220:223], v[244:247], v[48:63]
	v_mfma_f32_32x32x16_bf16 v[32:47], v[236:239], v[244:247], v[32:47]
	v_mfma_f32_32x32x16_bf16 v[16:31], v[220:223], v[248:251], v[16:31]
	v_mfma_f32_32x32x16_bf16 v[0:15], v[236:239], v[248:251], v[0:15]
	s_add_u32 s16, s16, 0x80
	s_addc_u32 s17, s17, 0
	s_add_i32 s22, s22, 1
	s_cmpk_lg_i32 s16, 0x800
	s_cbranch_scc1 .LpdP2_B
	s_branch .LBB0_394
